# sgu causal-mixing stage hand-written: all W fragment loads issued before the barrier, causal mask only on the diagonal iteration
# speedup vs baseline: 1.0053x; 1.0043x over previous
.LBB0_437:
	s_or_b64 exec, exec, s[0:1]
	s_lshr_b32 s0, s30, 3
	v_bfe_u32 v70, v60, 6, 2
	v_and_b32_e32 v82, 31, v66
	s_and_b32 s0, s0, 1
	v_ashrrev_i32_e32 v67, 8, v60
	v_lshlrev_b32_e32 v0, 3, v68
	v_lshl_or_b32 v1, v70, 6, v82
	v_lshl_add_u32 v3, v68, 4, 0
	v_mov_b32_e32 v63, 0
	s_lshl_b32 s2, s0, 2
	v_lshlrev_b32_e32 v69, 6, v67
	v_cmp_lt_i32_e32 vcc, -1, v67
	v_mad_u32_u24 v71, v1, s86, v3
	v_or_b32_e32 v72, 16, v0
	v_mov_b32_e32 v62, v63
	v_mov_b32_e32 v61, v63
	v_mov_b32_e32 v60, v63
	v_mov_b32_e32 v59, v63
	v_mov_b32_e32 v58, v63
	v_mov_b32_e32 v57, v63
	v_mov_b32_e32 v56, v63
	v_mov_b32_e32 v55, v63
	v_mov_b32_e32 v54, v63
	v_mov_b32_e32 v53, v63
	v_mov_b32_e32 v52, v63
	v_mov_b32_e32 v51, v63
	v_mov_b32_e32 v50, v63
	v_mov_b32_e32 v49, v63
	v_mov_b32_e32 v48, v63
	v_mov_b32_e32 v47, v63
	v_mov_b32_e32 v46, v63
	v_mov_b32_e32 v45, v63
	v_mov_b32_e32 v44, v63
	v_mov_b32_e32 v43, v63
	v_mov_b32_e32 v42, v63
	v_mov_b32_e32 v41, v63
	v_mov_b32_e32 v40, v63
	v_mov_b32_e32 v39, v63
	v_mov_b32_e32 v38, v63
	v_mov_b32_e32 v37, v63
	v_mov_b32_e32 v36, v63
	v_mov_b32_e32 v35, v63
	v_mov_b32_e32 v34, v63
	v_mov_b32_e32 v33, v63
	v_mov_b32_e32 v32, v63
	s_add_i32 s3, s21, s2
	v_add_u32_e32 v216, s3, v70
	v_lshlrev_b32_e32 v216, 16, v216
	v_add_u32_e32 v220, v69, v82
	v_lshl_add_u32 v216, v220, 9, v216
	v_and_b32_e32 v221, 32, v66
	v_add_u32_e32 v216, v216, v221
	v_mov_b32_e32 v217, 0
	v_lshl_add_u64 v[216:217], s[24:25], 0, v[216:217]
	s_mov_b64 s[26:27], 0x4000
	v_lshl_add_u64 v[218:219], v[216:217], 0, s[26:27]
	v_lshlrev_b32_e32 v220, 3, v68
	v_sub_u32_e32 v220, v82, v220
	v_add_u32_e32 v221, -16, v220
	v_readfirstlane_b32 s3, v67
	s_cmp_eq_u32 s3, 0
	s_cbranch_scc0 .Lsgu2_issue1
	global_load_dwordx4 v[88:91], v[216:217], off offset:-64
	global_load_dwordx4 v[92:95], v[216:217], off offset:-48
	global_load_dwordx4 v[96:99], v[216:217], off offset:0
	global_load_dwordx4 v[100:103], v[216:217], off offset:16
	global_load_dwordx4 v[104:107], v[218:219], off offset:-64
	global_load_dwordx4 v[108:111], v[218:219], off offset:-48
	global_load_dwordx4 v[112:115], v[218:219], off offset:0
	global_load_dwordx4 v[116:119], v[218:219], off offset:16
	global_load_dwordx4 v[120:123], v[218:219], off offset:64
	global_load_dwordx4 v[124:127], v[218:219], off offset:80
	global_load_dwordx4 v[128:131], v[218:219], off offset:128
	global_load_dwordx4 v[132:135], v[218:219], off offset:144
	s_branch .Lsgu2_issued
.Lsgu2_issue1:
	global_load_dwordx4 v[88:91], v[216:217], off offset:-64
	global_load_dwordx4 v[92:95], v[216:217], off offset:-48
	global_load_dwordx4 v[96:99], v[216:217], off offset:0
	global_load_dwordx4 v[100:103], v[216:217], off offset:16
	global_load_dwordx4 v[104:107], v[216:217], off offset:64
	global_load_dwordx4 v[108:111], v[216:217], off offset:80
	global_load_dwordx4 v[112:115], v[216:217], off offset:128
	global_load_dwordx4 v[116:119], v[216:217], off offset:144
	global_load_dwordx4 v[120:123], v[216:217], off offset:192
	global_load_dwordx4 v[124:127], v[216:217], off offset:208
	global_load_dwordx4 v[128:131], v[216:217], off offset:256
	global_load_dwordx4 v[132:135], v[216:217], off offset:272
	global_load_dwordx4 v[136:139], v[218:219], off offset:-64
	global_load_dwordx4 v[140:143], v[218:219], off offset:-48
	global_load_dwordx4 v[152:155], v[218:219], off offset:0
	global_load_dwordx4 v[156:159], v[218:219], off offset:16
	global_load_dwordx4 v[200:203], v[218:219], off offset:64
	global_load_dwordx4 v[204:207], v[218:219], off offset:80
	global_load_dwordx4 v[208:211], v[218:219], off offset:128
	global_load_dwordx4 v[212:215], v[218:219], off offset:144
	global_load_dwordx4 v[224:227], v[218:219], off offset:192
	global_load_dwordx4 v[228:231], v[218:219], off offset:208
	global_load_dwordx4 v[232:235], v[218:219], off offset:256
	global_load_dwordx4 v[236:239], v[218:219], off offset:272
.Lsgu2_issued:
	s_waitcnt lgkmcnt(0)
	s_barrier
	v_mov_b32_e32 v0, 0
	v_mov_b32_e32 v1, 0
	v_mov_b32_e32 v2, 0
	v_mov_b32_e32 v3, 0
	v_mov_b32_e32 v4, 0
	v_mov_b32_e32 v5, 0
	v_mov_b32_e32 v6, 0
	v_mov_b32_e32 v7, 0
	v_mov_b32_e32 v8, 0
	v_mov_b32_e32 v9, 0
	v_mov_b32_e32 v10, 0
	v_mov_b32_e32 v11, 0
	v_mov_b32_e32 v12, 0
	v_mov_b32_e32 v13, 0
	v_mov_b32_e32 v14, 0
	v_mov_b32_e32 v15, 0
	v_mov_b32_e32 v16, 0
	v_mov_b32_e32 v17, 0
	v_mov_b32_e32 v18, 0
	v_mov_b32_e32 v19, 0
	v_mov_b32_e32 v20, 0
	v_mov_b32_e32 v21, 0
	v_mov_b32_e32 v22, 0
	v_mov_b32_e32 v23, 0
	v_mov_b32_e32 v24, 0
	v_mov_b32_e32 v25, 0
	v_mov_b32_e32 v26, 0
	v_mov_b32_e32 v27, 0
	v_mov_b32_e32 v28, 0
	v_mov_b32_e32 v29, 0
	v_mov_b32_e32 v30, 0
	v_mov_b32_e32 v31, 0
	s_cmp_eq_u32 s3, 0
	s_cbranch_scc0 .Lsgu2_ph1
	ds_read_b128 v[240:243], v71
	ds_read_b128 v[244:247], v71 offset:8704
	s_waitcnt vmcnt(8)
	v_cmp_le_i32_e64 s[0:1], 0, v220
	v_cmp_le_i32_e64 s[2:3], 1, v220
	v_cmp_le_i32_e64 s[26:27], 2, v220
	v_cmp_le_i32_e64 s[28:29], 3, v220
	v_cndmask_b32_e64 v88, 0, v88, s[0:1]
	v_cndmask_b32_e64 v89, 0, v89, s[2:3]
	v_cndmask_b32_e64 v90, 0, v90, s[26:27]
	v_cndmask_b32_e64 v91, 0, v91, s[28:29]
	v_cmp_le_i32_e64 s[0:1], 4, v220
	v_cmp_le_i32_e64 s[2:3], 5, v220
	v_cmp_le_i32_e64 s[26:27], 6, v220
	v_cmp_le_i32_e64 s[28:29], 7, v220
	v_cndmask_b32_e64 v92, 0, v92, s[0:1]
	v_cndmask_b32_e64 v93, 0, v93, s[2:3]
	v_cndmask_b32_e64 v94, 0, v94, s[26:27]
	v_cndmask_b32_e64 v95, 0, v95, s[28:29]
	v_cmp_le_i32_e64 s[0:1], 0, v221
	v_cmp_le_i32_e64 s[2:3], 1, v221
	v_cmp_le_i32_e64 s[26:27], 2, v221
	v_cmp_le_i32_e64 s[28:29], 3, v221
	v_cndmask_b32_e64 v96, 0, v96, s[0:1]
	v_cndmask_b32_e64 v97, 0, v97, s[2:3]
	v_cndmask_b32_e64 v98, 0, v98, s[26:27]
	v_cndmask_b32_e64 v99, 0, v99, s[28:29]
	v_cmp_le_i32_e64 s[0:1], 4, v221
	v_cmp_le_i32_e64 s[2:3], 5, v221
	v_cmp_le_i32_e64 s[26:27], 6, v221
	v_cmp_le_i32_e64 s[28:29], 7, v221
	v_cndmask_b32_e64 v100, 0, v100, s[0:1]
	v_cndmask_b32_e64 v101, 0, v101, s[2:3]
	v_cndmask_b32_e64 v102, 0, v102, s[26:27]
	v_cndmask_b32_e64 v103, 0, v103, s[28:29]
	v_cvt_pk_bf16_f32 v88, v88, v89
	v_cvt_pk_bf16_f32 v89, v90, v91
	v_cvt_pk_bf16_f32 v90, v92, v93
	v_cvt_pk_bf16_f32 v91, v94, v95
	v_cvt_pk_bf16_f32 v96, v96, v97
	v_cvt_pk_bf16_f32 v97, v98, v99
	v_cvt_pk_bf16_f32 v98, v100, v101
	v_cvt_pk_bf16_f32 v99, v102, v103
	s_waitcnt lgkmcnt(0)
	v_mfma_f32_32x32x16_bf16 v[48:63], v[88:91], v[240:243], v[48:63]
	v_mfma_f32_32x32x16_bf16 v[32:47], v[88:91], v[244:247], v[32:47]
	ds_read_b128 v[240:243], v71 offset:32
	ds_read_b128 v[244:247], v71 offset:8736
	s_waitcnt lgkmcnt(0)
	v_mfma_f32_32x32x16_bf16 v[48:63], v[96:99], v[240:243], v[48:63]
	v_mfma_f32_32x32x16_bf16 v[32:47], v[96:99], v[244:247], v[32:47]
	ds_read_b128 v[240:243], v71
	ds_read_b128 v[244:247], v71 offset:8704
	s_waitcnt vmcnt(4)
	v_cvt_pk_bf16_f32 v104, v104, v105
	v_cvt_pk_bf16_f32 v105, v106, v107
	v_cvt_pk_bf16_f32 v106, v108, v109
	v_cvt_pk_bf16_f32 v107, v110, v111
	v_cvt_pk_bf16_f32 v112, v112, v113
	v_cvt_pk_bf16_f32 v113, v114, v115
	v_cvt_pk_bf16_f32 v114, v116, v117
	v_cvt_pk_bf16_f32 v115, v118, v119
	s_waitcnt lgkmcnt(0)
	v_mfma_f32_32x32x16_bf16 v[16:31], v[104:107], v[240:243], v[16:31]
	v_mfma_f32_32x32x16_bf16 v[0:15], v[104:107], v[244:247], v[0:15]
	ds_read_b128 v[240:243], v71 offset:32
	ds_read_b128 v[244:247], v71 offset:8736
	s_waitcnt lgkmcnt(0)
	v_mfma_f32_32x32x16_bf16 v[16:31], v[112:115], v[240:243], v[16:31]
	v_mfma_f32_32x32x16_bf16 v[0:15], v[112:115], v[244:247], v[0:15]
	ds_read_b128 v[240:243], v71 offset:64
	ds_read_b128 v[244:247], v71 offset:8768
	s_waitcnt vmcnt(0)
	v_cmp_le_i32_e64 s[0:1], 0, v220
	v_cmp_le_i32_e64 s[2:3], 1, v220
	v_cmp_le_i32_e64 s[26:27], 2, v220
	v_cmp_le_i32_e64 s[28:29], 3, v220
	v_cndmask_b32_e64 v120, 0, v120, s[0:1]
	v_cndmask_b32_e64 v121, 0, v121, s[2:3]
	v_cndmask_b32_e64 v122, 0, v122, s[26:27]
	v_cndmask_b32_e64 v123, 0, v123, s[28:29]
	v_cmp_le_i32_e64 s[0:1], 4, v220
	v_cmp_le_i32_e64 s[2:3], 5, v220
	v_cmp_le_i32_e64 s[26:27], 6, v220
	v_cmp_le_i32_e64 s[28:29], 7, v220
	v_cndmask_b32_e64 v124, 0, v124, s[0:1]
	v_cndmask_b32_e64 v125, 0, v125, s[2:3]
	v_cndmask_b32_e64 v126, 0, v126, s[26:27]
	v_cndmask_b32_e64 v127, 0, v127, s[28:29]
	v_cmp_le_i32_e64 s[0:1], 0, v221
	v_cmp_le_i32_e64 s[2:3], 1, v221
	v_cmp_le_i32_e64 s[26:27], 2, v221
	v_cmp_le_i32_e64 s[28:29], 3, v221
	v_cndmask_b32_e64 v128, 0, v128, s[0:1]
	v_cndmask_b32_e64 v129, 0, v129, s[2:3]
	v_cndmask_b32_e64 v130, 0, v130, s[26:27]
	v_cndmask_b32_e64 v131, 0, v131, s[28:29]
	v_cmp_le_i32_e64 s[0:1], 4, v221
	v_cmp_le_i32_e64 s[2:3], 5, v221
	v_cmp_le_i32_e64 s[26:27], 6, v221
	v_cmp_le_i32_e64 s[28:29], 7, v221
	v_cndmask_b32_e64 v132, 0, v132, s[0:1]
	v_cndmask_b32_e64 v133, 0, v133, s[2:3]
	v_cndmask_b32_e64 v134, 0, v134, s[26:27]
	v_cndmask_b32_e64 v135, 0, v135, s[28:29]
	v_cvt_pk_bf16_f32 v120, v120, v121
	v_cvt_pk_bf16_f32 v121, v122, v123
	v_cvt_pk_bf16_f32 v122, v124, v125
	v_cvt_pk_bf16_f32 v123, v126, v127
	v_cvt_pk_bf16_f32 v128, v128, v129
	v_cvt_pk_bf16_f32 v129, v130, v131
	v_cvt_pk_bf16_f32 v130, v132, v133
	v_cvt_pk_bf16_f32 v131, v134, v135
	s_waitcnt lgkmcnt(0)
	v_mfma_f32_32x32x16_bf16 v[16:31], v[120:123], v[240:243], v[16:31]
	v_mfma_f32_32x32x16_bf16 v[0:15], v[120:123], v[244:247], v[0:15]
	ds_read_b128 v[240:243], v71 offset:96
	ds_read_b128 v[244:247], v71 offset:8800
	s_waitcnt lgkmcnt(0)
	v_mfma_f32_32x32x16_bf16 v[16:31], v[128:131], v[240:243], v[16:31]
	v_mfma_f32_32x32x16_bf16 v[0:15], v[128:131], v[244:247], v[0:15]
	s_branch .LBB0_404
.Lsgu2_ph1:
	ds_read_b128 v[240:243], v71
	ds_read_b128 v[244:247], v71 offset:8704
	s_waitcnt vmcnt(20)
	v_cvt_pk_bf16_f32 v88, v88, v89
	v_cvt_pk_bf16_f32 v89, v90, v91
	v_cvt_pk_bf16_f32 v90, v92, v93
	v_cvt_pk_bf16_f32 v91, v94, v95
	v_cvt_pk_bf16_f32 v96, v96, v97
	v_cvt_pk_bf16_f32 v97, v98, v99
	v_cvt_pk_bf16_f32 v98, v100, v101
	v_cvt_pk_bf16_f32 v99, v102, v103
	s_waitcnt lgkmcnt(0)
	v_mfma_f32_32x32x16_bf16 v[48:63], v[88:91], v[240:243], v[48:63]
	v_mfma_f32_32x32x16_bf16 v[32:47], v[88:91], v[244:247], v[32:47]
	ds_read_b128 v[240:243], v71 offset:32
	ds_read_b128 v[244:247], v71 offset:8736
	s_waitcnt lgkmcnt(0)
	v_mfma_f32_32x32x16_bf16 v[48:63], v[96:99], v[240:243], v[48:63]
	v_mfma_f32_32x32x16_bf16 v[32:47], v[96:99], v[244:247], v[32:47]
	global_load_dwordx4 v[88:91], v[218:219], off offset:320
	global_load_dwordx4 v[92:95], v[218:219], off offset:336
	global_load_dwordx4 v[96:99], v[218:219], off offset:384
	global_load_dwordx4 v[100:103], v[218:219], off offset:400
	ds_read_b128 v[240:243], v71 offset:64
	ds_read_b128 v[244:247], v71 offset:8768
	s_waitcnt vmcnt(20)
	v_cvt_pk_bf16_f32 v104, v104, v105
	v_cvt_pk_bf16_f32 v105, v106, v107
	v_cvt_pk_bf16_f32 v106, v108, v109
	v_cvt_pk_bf16_f32 v107, v110, v111
	v_cvt_pk_bf16_f32 v112, v112, v113
	v_cvt_pk_bf16_f32 v113, v114, v115
	v_cvt_pk_bf16_f32 v114, v116, v117
	v_cvt_pk_bf16_f32 v115, v118, v119
	s_waitcnt lgkmcnt(0)
	v_mfma_f32_32x32x16_bf16 v[48:63], v[104:107], v[240:243], v[48:63]
	v_mfma_f32_32x32x16_bf16 v[32:47], v[104:107], v[244:247], v[32:47]
	ds_read_b128 v[240:243], v71 offset:96
	ds_read_b128 v[244:247], v71 offset:8800
	s_waitcnt lgkmcnt(0)
	v_mfma_f32_32x32x16_bf16 v[48:63], v[112:115], v[240:243], v[48:63]
	v_mfma_f32_32x32x16_bf16 v[32:47], v[112:115], v[244:247], v[32:47]
	ds_read_b128 v[240:243], v71 offset:128
	ds_read_b128 v[244:247], v71 offset:8832
	s_waitcnt vmcnt(16)
	v_cmp_le_i32_e64 s[0:1], 0, v220
	v_cmp_le_i32_e64 s[2:3], 1, v220
	v_cmp_le_i32_e64 s[26:27], 2, v220
	v_cmp_le_i32_e64 s[28:29], 3, v220
	v_cndmask_b32_e64 v120, 0, v120, s[0:1]
	v_cndmask_b32_e64 v121, 0, v121, s[2:3]
	v_cndmask_b32_e64 v122, 0, v122, s[26:27]
	v_cndmask_b32_e64 v123, 0, v123, s[28:29]
	v_cmp_le_i32_e64 s[0:1], 4, v220
	v_cmp_le_i32_e64 s[2:3], 5, v220
	v_cmp_le_i32_e64 s[26:27], 6, v220
	v_cmp_le_i32_e64 s[28:29], 7, v220
	v_cndmask_b32_e64 v124, 0, v124, s[0:1]
	v_cndmask_b32_e64 v125, 0, v125, s[2:3]
	v_cndmask_b32_e64 v126, 0, v126, s[26:27]
	v_cndmask_b32_e64 v127, 0, v127, s[28:29]
	v_cmp_le_i32_e64 s[0:1], 0, v221
	v_cmp_le_i32_e64 s[2:3], 1, v221
	v_cmp_le_i32_e64 s[26:27], 2, v221
	v_cmp_le_i32_e64 s[28:29], 3, v221
	v_cndmask_b32_e64 v128, 0, v128, s[0:1]
	v_cndmask_b32_e64 v129, 0, v129, s[2:3]
	v_cndmask_b32_e64 v130, 0, v130, s[26:27]
	v_cndmask_b32_e64 v131, 0, v131, s[28:29]
	v_cmp_le_i32_e64 s[0:1], 4, v221
	v_cmp_le_i32_e64 s[2:3], 5, v221
	v_cmp_le_i32_e64 s[26:27], 6, v221
	v_cmp_le_i32_e64 s[28:29], 7, v221
	v_cndmask_b32_e64 v132, 0, v132, s[0:1]
	v_cndmask_b32_e64 v133, 0, v133, s[2:3]
	v_cndmask_b32_e64 v134, 0, v134, s[26:27]
	v_cndmask_b32_e64 v135, 0, v135, s[28:29]
	v_cvt_pk_bf16_f32 v120, v120, v121
	v_cvt_pk_bf16_f32 v121, v122, v123
	v_cvt_pk_bf16_f32 v122, v124, v125
	v_cvt_pk_bf16_f32 v123, v126, v127
	v_cvt_pk_bf16_f32 v128, v128, v129
	v_cvt_pk_bf16_f32 v129, v130, v131
	v_cvt_pk_bf16_f32 v130, v132, v133
	v_cvt_pk_bf16_f32 v131, v134, v135
	s_waitcnt lgkmcnt(0)
	v_mfma_f32_32x32x16_bf16 v[48:63], v[120:123], v[240:243], v[48:63]
	v_mfma_f32_32x32x16_bf16 v[32:47], v[120:123], v[244:247], v[32:47]
	ds_read_b128 v[240:243], v71 offset:160
	ds_read_b128 v[244:247], v71 offset:8864
	s_waitcnt lgkmcnt(0)
	v_mfma_f32_32x32x16_bf16 v[48:63], v[128:131], v[240:243], v[48:63]
	v_mfma_f32_32x32x16_bf16 v[32:47], v[128:131], v[244:247], v[32:47]
	ds_read_b128 v[240:243], v71
	ds_read_b128 v[244:247], v71 offset:8704
	s_waitcnt vmcnt(12)
	v_cvt_pk_bf16_f32 v136, v136, v137
	v_cvt_pk_bf16_f32 v137, v138, v139
	v_cvt_pk_bf16_f32 v138, v140, v141
	v_cvt_pk_bf16_f32 v139, v142, v143
	v_cvt_pk_bf16_f32 v152, v152, v153
	v_cvt_pk_bf16_f32 v153, v154, v155
	v_cvt_pk_bf16_f32 v154, v156, v157
	v_cvt_pk_bf16_f32 v155, v158, v159
	s_waitcnt lgkmcnt(0)
	v_mfma_f32_32x32x16_bf16 v[16:31], v[136:139], v[240:243], v[16:31]
	v_mfma_f32_32x32x16_bf16 v[0:15], v[136:139], v[244:247], v[0:15]
	ds_read_b128 v[240:243], v71 offset:32
	ds_read_b128 v[244:247], v71 offset:8736
	s_waitcnt lgkmcnt(0)
	v_mfma_f32_32x32x16_bf16 v[16:31], v[152:155], v[240:243], v[16:31]
	v_mfma_f32_32x32x16_bf16 v[0:15], v[152:155], v[244:247], v[0:15]
	ds_read_b128 v[240:243], v71 offset:64
	ds_read_b128 v[244:247], v71 offset:8768
	s_waitcnt vmcnt(8)
	v_cvt_pk_bf16_f32 v200, v200, v201
	v_cvt_pk_bf16_f32 v201, v202, v203
	v_cvt_pk_bf16_f32 v202, v204, v205
	v_cvt_pk_bf16_f32 v203, v206, v207
	v_cvt_pk_bf16_f32 v208, v208, v209
	v_cvt_pk_bf16_f32 v209, v210, v211
	v_cvt_pk_bf16_f32 v210, v212, v213
	v_cvt_pk_bf16_f32 v211, v214, v215
	s_waitcnt lgkmcnt(0)
	v_mfma_f32_32x32x16_bf16 v[16:31], v[200:203], v[240:243], v[16:31]
	v_mfma_f32_32x32x16_bf16 v[0:15], v[200:203], v[244:247], v[0:15]
	ds_read_b128 v[240:243], v71 offset:96
	ds_read_b128 v[244:247], v71 offset:8800
	s_waitcnt lgkmcnt(0)
	v_mfma_f32_32x32x16_bf16 v[16:31], v[208:211], v[240:243], v[16:31]
	v_mfma_f32_32x32x16_bf16 v[0:15], v[208:211], v[244:247], v[0:15]
	ds_read_b128 v[240:243], v71 offset:128
	ds_read_b128 v[244:247], v71 offset:8832
	s_waitcnt vmcnt(4)
	v_cvt_pk_bf16_f32 v224, v224, v225
	v_cvt_pk_bf16_f32 v225, v226, v227
	v_cvt_pk_bf16_f32 v226, v228, v229
	v_cvt_pk_bf16_f32 v227, v230, v231
	v_cvt_pk_bf16_f32 v232, v232, v233
	v_cvt_pk_bf16_f32 v233, v234, v235
	v_cvt_pk_bf16_f32 v234, v236, v237
	v_cvt_pk_bf16_f32 v235, v238, v239
	s_waitcnt lgkmcnt(0)
	v_mfma_f32_32x32x16_bf16 v[16:31], v[224:227], v[240:243], v[16:31]
	v_mfma_f32_32x32x16_bf16 v[0:15], v[224:227], v[244:247], v[0:15]
	ds_read_b128 v[240:243], v71 offset:160
	ds_read_b128 v[244:247], v71 offset:8864
	s_waitcnt lgkmcnt(0)
	v_mfma_f32_32x32x16_bf16 v[16:31], v[232:235], v[240:243], v[16:31]
	v_mfma_f32_32x32x16_bf16 v[0:15], v[232:235], v[244:247], v[0:15]
	ds_read_b128 v[240:243], v71 offset:192
	ds_read_b128 v[244:247], v71 offset:8896
	s_waitcnt vmcnt(0)
	v_cmp_le_i32_e64 s[0:1], 0, v220
	v_cmp_le_i32_e64 s[2:3], 1, v220
	v_cmp_le_i32_e64 s[26:27], 2, v220
	v_cmp_le_i32_e64 s[28:29], 3, v220
	v_cndmask_b32_e64 v88, 0, v88, s[0:1]
	v_cndmask_b32_e64 v89, 0, v89, s[2:3]
	v_cndmask_b32_e64 v90, 0, v90, s[26:27]
	v_cndmask_b32_e64 v91, 0, v91, s[28:29]
	v_cmp_le_i32_e64 s[0:1], 4, v220
	v_cmp_le_i32_e64 s[2:3], 5, v220
	v_cmp_le_i32_e64 s[26:27], 6, v220
	v_cmp_le_i32_e64 s[28:29], 7, v220
	v_cndmask_b32_e64 v92, 0, v92, s[0:1]
	v_cndmask_b32_e64 v93, 0, v93, s[2:3]
	v_cndmask_b32_e64 v94, 0, v94, s[26:27]
	v_cndmask_b32_e64 v95, 0, v95, s[28:29]
	v_cmp_le_i32_e64 s[0:1], 0, v221
	v_cmp_le_i32_e64 s[2:3], 1, v221
	v_cmp_le_i32_e64 s[26:27], 2, v221
	v_cmp_le_i32_e64 s[28:29], 3, v221
	v_cndmask_b32_e64 v96, 0, v96, s[0:1]
	v_cndmask_b32_e64 v97, 0, v97, s[2:3]
	v_cndmask_b32_e64 v98, 0, v98, s[26:27]
	v_cndmask_b32_e64 v99, 0, v99, s[28:29]
	v_cmp_le_i32_e64 s[0:1], 4, v221
	v_cmp_le_i32_e64 s[2:3], 5, v221
	v_cmp_le_i32_e64 s[26:27], 6, v221
	v_cmp_le_i32_e64 s[28:29], 7, v221
	v_cndmask_b32_e64 v100, 0, v100, s[0:1]
	v_cndmask_b32_e64 v101, 0, v101, s[2:3]
	v_cndmask_b32_e64 v102, 0, v102, s[26:27]
	v_cndmask_b32_e64 v103, 0, v103, s[28:29]
	v_cvt_pk_bf16_f32 v88, v88, v89
	v_cvt_pk_bf16_f32 v89, v90, v91
	v_cvt_pk_bf16_f32 v90, v92, v93
	v_cvt_pk_bf16_f32 v91, v94, v95
	v_cvt_pk_bf16_f32 v96, v96, v97
	v_cvt_pk_bf16_f32 v97, v98, v99
	v_cvt_pk_bf16_f32 v98, v100, v101
	v_cvt_pk_bf16_f32 v99, v102, v103
	s_waitcnt lgkmcnt(0)
	v_mfma_f32_32x32x16_bf16 v[16:31], v[88:91], v[240:243], v[16:31]
	v_mfma_f32_32x32x16_bf16 v[0:15], v[88:91], v[244:247], v[0:15]
	ds_read_b128 v[240:243], v71 offset:224
	ds_read_b128 v[244:247], v71 offset:8928
	s_waitcnt lgkmcnt(0)
	v_mfma_f32_32x32x16_bf16 v[16:31], v[96:99], v[240:243], v[16:31]
	v_mfma_f32_32x32x16_bf16 v[0:15], v[96:99], v[244:247], v[0:15]
	s_branch .LBB0_404
